# P5 slack filling with two weight items per wave (3968 FFN2 gate/up items moved out of P0)
# baseline (speedup 1.0000x reference)
; __global__ void __launch_bounds__(NTHREADS, 2) fwd_kernel(Params P) {
;     ...
;         for (int it = gw; it < IT_TOTAL; it += NGW) {
;             int r = it; const float* W; bf16_t* WT; int N, ldk, mode = 0; const float* fg = nullptr; const float* fb = nullptr; float* cs = nullptr;
;             if (r < IT_GU) { W = P.in[I_WIN]; WT = WIN; N = NZ; ldk = D; fg = P.in[I_LN1G]; fb = P.in[I_LN1B]; cs = CSUM; }
;             else if ((r -= IT_GU) < IT_SQ) { W = P.in[I_WKV]; WT = WKV; N = D; ldk = D; }
;             else if ((r -= IT_SQ) < 3 * IT_BR) { const int k = r / IT_BR; r -= k * IT_BR; W = P.in[I_WBR] + (size_t)k * BW * D; WT = WBR + (size_t)k * D * BW; N = D; ldk = BW; }
;             else if ((r -= 3 * IT_BR) < IT_SQ) { W = P.in[I_WOUT]; WT = WOUT; N = D; ldk = D; }
;             else if ((r -= IT_SQ) < IT_GU) { W = P.in[I_GU2]; WT = WGU2; N = NZ; ldk = D; mode = 1; fg = P.in[I_LN2G]; fb = P.in[I_LN2B]; cs = CSUM + 2 * NZ; }
;             else if ((r -= IT_GU) < IT_DN) { W = P.in[I_DN2]; WT = WD2; N = D; ldk = FF; }
;             else if ((r -= IT_DN) < 16 * IT_LR) { const int m = r / IT_LR; r -= m * IT_LR; const int k = m >> 1, x = m & 1;
;                 W = (x ? P.in[I_LWX] : P.in[I_LWA]) + (size_t)k * 128 * 128; WT = WLRU + (size_t)k * 256 * 128 + x * 128 * 128; N = 128; ldk = 128; }
;             else if ((r -= 16 * IT_LR) < IT_DN) { W = P.in[I_DN1]; WT = WD1; N = D; ldk = FF; }
;             else { r -= IT_DN; W = P.in[I_GU1]; WT = WGU1; N = NZ; ldk = D; mode = 1; }
;             const int nblk = N / 32, kb = r / nblk, nb = r % nblk, n0 = 32 * nb;
;             int dr = n0;
;             if (mode == 1) dr = (n0 < FF) ? (n0 / 128) * 256 + (n0 % 128) : ((n0 - FF) / 128) * 256 + 128 + ((n0 - FF) % 128);
;             transpose_item(W, N, WT, ldk, 64 * kb, n0, dr, scr, lane, fg, fb, cs);
;         }
.Lcv_exit:
	s_cmp_lg_u32 s100, 0
	s_cbranch_scc1 .Lcv_d1
	s_mov_b32 s100, 1
	s_mov_b32 s98, 0x73ff
	v_readlane_b32 s99, v255, 13
	s_lshl_b32 s101, s34, 3
	s_nop 3
	s_add_i32 s99, s99, s101
	s_add_i32 s99, s99, 0x400
	s_and_b32 s99, s99, 0x7ff
	s_add_i32 s30, s99, 0x6680
	s_branch .Lcv_entry

; __device__ __forceinline__ void xcd_barrier(const XcdBarrier& b) {
;     asm volatile("s_waitcnt vmcnt(0)" ::: "memory");
;     __syncthreads();
; __global__ void __launch_bounds__(NTHREADS, 2) fwd_kernel(Params P) {
;     ...
;         for (int it = gw; it < IT_TOTAL; it += NGW) {
;             int r = it; const float* W; bf16_t* WT; int N, ldk, mode = 0; const float* fg = nullptr; const float* fb = nullptr; float* cs = nullptr;
;             if (r < IT_GU) { W = P.in[I_WIN]; WT = WIN; N = NZ; ldk = D; fg = P.in[I_LN1G]; fb = P.in[I_LN1B]; cs = CSUM; }
;             else if ((r -= IT_GU) < IT_SQ) { W = P.in[I_WKV]; WT = WKV; N = D; ldk = D; }
;             else if ((r -= IT_SQ) < 3 * IT_BR) { const int k = r / IT_BR; r -= k * IT_BR; W = P.in[I_WBR] + (size_t)k * BW * D; WT = WBR + (size_t)k * D * BW; N = D; ldk = BW; }
;             else if ((r -= 3 * IT_BR) < IT_SQ) { W = P.in[I_WOUT]; WT = WOUT; N = D; ldk = D; }
;             else if ((r -= IT_SQ) < IT_GU) { W = P.in[I_GU2]; WT = WGU2; N = NZ; ldk = D; mode = 1; fg = P.in[I_LN2G]; fb = P.in[I_LN2B]; cs = CSUM + 2 * NZ; }
;             else if ((r -= IT_GU) < IT_DN) { W = P.in[I_DN2]; WT = WD2; N = D; ldk = FF; }
;             else if ((r -= IT_DN) < 16 * IT_LR) { const int m = r / IT_LR; r -= m * IT_LR; const int k = m >> 1, x = m & 1;
;                 W = (x ? P.in[I_LWX] : P.in[I_LWA]) + (size_t)k * 128 * 128; WT = WLRU + (size_t)k * 256 * 128 + x * 128 * 128; N = 128; ldk = 128; }
;             else if ((r -= 16 * IT_LR) < IT_DN) { W = P.in[I_DN1]; WT = WD1; N = D; ldk = FF; }
;             else { r -= IT_DN; W = P.in[I_GU1]; WT = WGU1; N = NZ; ldk = D; mode = 1; }
;             const int nblk = N / 32, kb = r / nblk, nb = r % nblk, n0 = 32 * nb;
;             int dr = n0;
;             if (mode == 1) dr = (n0 < FF) ? (n0 / 128) * 256 + (n0 % 128) : ((n0 - FF) / 128) * 256 + 128 + ((n0 - FF) % 128);
;             transpose_item(W, N, WT, ldk, 64 * kb, n0, dr, scr, lane, fg, fb, cs);
;         }
.LBB0_641:
	s_waitcnt vmcnt(0)
	s_barrier
	s_cmp_lt_u32 s34, 8
	s_cbranch_scc1 .Lcv_skip_p5
	v_writelane_b32 v252, s0, 0
	v_writelane_b32 v252, s1, 1
	v_writelane_b32 v252, s2, 2
	v_writelane_b32 v252, s3, 3
	v_writelane_b32 v252, s4, 4
	v_writelane_b32 v252, s5, 5
	v_writelane_b32 v252, s6, 6
	v_writelane_b32 v252, s7, 7
	v_writelane_b32 v252, s8, 8
	v_writelane_b32 v252, s9, 9
	v_writelane_b32 v252, s10, 10
	v_writelane_b32 v252, s11, 11
	v_writelane_b32 v252, s12, 12
	v_writelane_b32 v252, s13, 13
	v_writelane_b32 v252, s14, 14
	v_writelane_b32 v252, s15, 15
	v_writelane_b32 v252, s16, 16
	v_writelane_b32 v252, s17, 17
	v_writelane_b32 v252, s18, 18
	v_writelane_b32 v252, s19, 19
	v_writelane_b32 v252, s20, 20
	v_writelane_b32 v252, s21, 21
	v_writelane_b32 v252, s22, 22
	v_writelane_b32 v252, s23, 23
	v_writelane_b32 v252, s24, 24
	v_writelane_b32 v252, s25, 25
	v_writelane_b32 v252, s26, 26
	v_writelane_b32 v252, s27, 27
	v_writelane_b32 v252, s28, 28
	v_writelane_b32 v252, s29, 29
	v_writelane_b32 v252, s30, 30
	v_writelane_b32 v252, s31, 31
	v_writelane_b32 v252, s32, 32
	v_writelane_b32 v252, s33, 33
	v_writelane_b32 v252, s34, 34
	v_writelane_b32 v252, s35, 35
	v_writelane_b32 v252, s36, 36
	v_writelane_b32 v252, s37, 37
	v_writelane_b32 v252, s38, 38
	v_writelane_b32 v252, s39, 39
	v_writelane_b32 v252, s40, 40
	v_writelane_b32 v252, s41, 41
	v_writelane_b32 v252, s42, 42
	v_writelane_b32 v252, s43, 43
	v_writelane_b32 v252, s44, 44
	v_writelane_b32 v252, s45, 45
	v_writelane_b32 v252, s46, 46
	v_writelane_b32 v252, s47, 47
	v_writelane_b32 v252, s48, 48
	v_writelane_b32 v252, s49, 49
	v_writelane_b32 v252, s50, 50
	v_writelane_b32 v252, s51, 51
	v_writelane_b32 v252, s52, 52
	v_writelane_b32 v252, s53, 53
	v_writelane_b32 v252, s54, 54
	v_writelane_b32 v252, s55, 55
	v_writelane_b32 v252, s56, 56
	v_writelane_b32 v252, s57, 57
	v_writelane_b32 v252, s58, 58
	v_writelane_b32 v252, s59, 59
	v_writelane_b32 v252, s60, 60
	v_writelane_b32 v252, s61, 61
	v_writelane_b32 v252, s62, 62
	v_writelane_b32 v252, s63, 63
	v_writelane_b32 v253, s64, 0
	v_writelane_b32 v253, s65, 1
	v_writelane_b32 v253, s66, 2
	v_writelane_b32 v253, s67, 3
	v_writelane_b32 v253, s68, 4
	v_writelane_b32 v253, s69, 5
	v_writelane_b32 v253, s70, 6
	v_writelane_b32 v253, s71, 7
	v_writelane_b32 v253, s72, 8
	v_writelane_b32 v253, s73, 9
	v_writelane_b32 v253, s74, 10
	v_writelane_b32 v253, s75, 11
	v_writelane_b32 v253, s76, 12
	v_writelane_b32 v253, s77, 13
	v_writelane_b32 v253, s78, 14
	v_writelane_b32 v253, s79, 15
	v_writelane_b32 v253, s80, 16
	v_writelane_b32 v253, s81, 17
	v_writelane_b32 v253, s82, 18
	v_writelane_b32 v253, s83, 19
	v_writelane_b32 v253, s84, 20
	v_writelane_b32 v253, s85, 21
	v_writelane_b32 v253, s86, 22
	v_writelane_b32 v253, s87, 23
	v_writelane_b32 v253, s88, 24
	v_writelane_b32 v253, s89, 25
	v_writelane_b32 v253, s90, 26
	v_writelane_b32 v253, s91, 27
	v_writelane_b32 v253, s92, 28
	v_writelane_b32 v253, s93, 29
	v_writelane_b32 v253, s94, 30
	v_writelane_b32 v253, s95, 31
	v_writelane_b32 v253, s96, 32
	v_writelane_b32 v253, s97, 33
	s_mov_b32 s100, 5
	s_mov_b32 s98, 0x667f
	v_and_b32_e32 v237, 63, v178
	v_readlane_b32 s99, v255, 13
	v_readfirstlane_b32 s37, v178
	s_nop 4
	s_sub_i32 s101, s34, 8
	s_lshl_b32 s101, s101, 3
	s_add_i32 s99, s99, s101
	s_add_i32 s30, s99, 0x5700
	s_movk_i32 s86, 1984
	s_branch .Lcv_hop_entry
